# 128 KiB seam code warm-up (was 64 KiB), stacked on v85
# speedup vs baseline: 1.0003x; 1.0003x over previous
.Lcpf_pc_0:
	s_add_u32 s98, s98, .LBB0_189-.Lcpf_pc_0
	s_addc_u32 s99, s99, 0
	v_lshlrev_b32_e32 v252, 7, v186
	global_load_dword v253, v252, s[98:99]
	s_add_u32 s98, s98, 0x2000
	s_addc_u32 s99, s99, 0
	global_load_dword v253, v252, s[98:99]
	s_add_u32 s98, s98, 0x2000
	s_addc_u32 s99, s99, 0
	global_load_dword v253, v252, s[98:99]
	s_add_u32 s98, s98, 0x2000
	s_addc_u32 s99, s99, 0
	global_load_dword v253, v252, s[98:99]
	s_add_u32 s98, s98, 0x2000
	s_addc_u32 s99, s99, 0
	global_load_dword v253, v252, s[98:99]
	s_add_u32 s98, s98, 0x2000
	s_addc_u32 s99, s99, 0
	global_load_dword v253, v252, s[98:99]
	s_add_u32 s98, s98, 0x2000
	s_addc_u32 s99, s99, 0
	global_load_dword v253, v252, s[98:99]
	s_add_u32 s98, s98, 0x2000
	s_addc_u32 s99, s99, 0
	global_load_dword v253, v252, s[98:99]
	s_add_u32 s98, s98, 0x2000
	s_addc_u32 s99, s99, 0
	global_load_dword v253, v252, s[98:99]
	s_add_u32 s98, s98, 0x2000
	s_addc_u32 s99, s99, 0
	global_load_dword v253, v252, s[98:99]
	s_add_u32 s98, s98, 0x2000
	s_addc_u32 s99, s99, 0
	global_load_dword v253, v252, s[98:99]
	s_add_u32 s98, s98, 0x2000
	s_addc_u32 s99, s99, 0
	global_load_dword v253, v252, s[98:99]
	s_add_u32 s98, s98, 0x2000
	s_addc_u32 s99, s99, 0
	global_load_dword v253, v252, s[98:99]
	s_add_u32 s98, s98, 0x2000
	s_addc_u32 s99, s99, 0
	global_load_dword v253, v252, s[98:99]
	s_add_u32 s98, s98, 0x2000
	s_addc_u32 s99, s99, 0
	global_load_dword v253, v252, s[98:99]
	s_add_u32 s98, s98, 0x2000
	s_addc_u32 s99, s99, 0
	global_load_dword v253, v252, s[98:99]
